# mode-B fast loop, first half-iteration software-pipelined: first accumulator's four k-steps first, its 16 exps issued under the second accumulator's QK MFMAs
# baseline (speedup 1.0000x reference)
; DI f32x16 mfma(bf16x8 a, bf16x8 b, f32x16 c) { return __builtin_amdgcn_mfma_f32_32x32x16_bf16(a, b, c, 0, 0, 0); }
; template <int MODE>
; DI void attn_tile(const Params& p, int layer, int tile, char* smem) {
;     ...
;       const u16* Kb = Ks + buf * 64 * KROW + r * KROW + 8 * h;
;       const u16* Vb = Vs + buf * 64 * VROW;
;       bf16x8 vf[8];
; #pragma unroll
;       for (int cs2 = 0; cs2 < 4; ++cs2) {
;         const u16* vp = Vb + (16 * cs2 + 4 * h + qq) * VROW + 16 * g16 + 4 * pp4;
;         { s16x4 lo = tr_read(vp), hi = tr_read(vp + 8 * VROW); vf[2 * cs2] = __builtin_shufflevector(lo, hi, 0, 1, 2, 3, 4, 5, 6, 7); }
;         { s16x4 lo = tr_read(vp + 32), hi = tr_read(vp + 8 * VROW + 32); vf[2 * cs2 + 1] = __builtin_shufflevector(lo, hi, 0, 1, 2, 3, 4, 5, 6, 7); }
;       }
;       f32x16 s0 = negm, s1 = negm;
; #pragma unroll
;       for (int d0 = 0; d0 < NKQ; ++d0) {
;         bf16x8 k0 = *(const bf16x8*)(Kb + d0 * 16);
;         bf16x8 k1 = *(const bf16x8*)(Kb + 32 * KROW + d0 * 16);
;         s0 = mfma(k0, qf[d0], s0);
;         s1 = mfma(k1, qf[d0], s1);
;       }
.Lfast_b:
	ds_read_b128 v[50:53], v174
	ds_read_b128 v[54:57], v174 offset:32
	ds_read_b128 v[58:61], v174 offset:64
	ds_read_b128 v[220:223], v174 offset:96
	ds_read_b128 v[224:227], v174 offset:4608
	ds_read_b128 v[228:231], v174 offset:4640
	ds_read_b128 v[236:239], v174 offset:4672
	ds_read_b128 v[240:243], v174 offset:4704
	s_waitcnt lgkmcnt(7)
	v_mfma_f32_32x32x16_bf16 v[66:81], v[50:53], v[98:101], v[34:49]
	s_waitcnt lgkmcnt(6)
	v_mfma_f32_32x32x16_bf16 v[66:81], v[54:57], v[102:105], v[66:81]
	ds_read_b64_tr_b16 v[158:159], v173 offset:26624
	ds_read_b64_tr_b16 v[160:161], v173 offset:27776
	ds_read_b64_tr_b16 v[156:157], v173 offset:27840
	ds_read_b64_tr_b16 v[154:155], v173 offset:26688
	ds_read_b64_tr_b16 v[150:151], v173 offset:28928
	ds_read_b64_tr_b16 v[152:153], v173 offset:30080
	ds_read_b64_tr_b16 v[148:149], v173 offset:30144
	ds_read_b64_tr_b16 v[146:147], v173 offset:28992
	s_waitcnt lgkmcnt(13)
	v_mfma_f32_32x32x16_bf16 v[66:81], v[58:61], v[106:109], v[66:81]
	s_waitcnt lgkmcnt(12)
	v_mfma_f32_32x32x16_bf16 v[66:81], v[220:223], v[110:113], v[66:81]
	ds_read_b64_tr_b16 v[142:143], v173 offset:31232
	ds_read_b64_tr_b16 v[144:145], v173 offset:32384
	ds_read_b64_tr_b16 v[140:141], v173 offset:32448
	ds_read_b64_tr_b16 v[138:139], v173 offset:31296
	ds_read_b64_tr_b16 v[130:131], v173 offset:33536
	ds_read_b64_tr_b16 v[132:133], v173 offset:34688
	ds_read_b64_tr_b16 v[136:137], v173 offset:34752
	ds_read_b64_tr_b16 v[134:135], v173 offset:33600
	s_waitcnt lgkmcnt(15)
	v_mfma_f32_32x32x16_bf16 v[82:97], v[224:227], v[98:101], v[34:49]
	s_and_saveexec_b64 s[0:1], s[6:7]
	s_cbranch_execz .Lstf_b_s1skip
	s_waitcnt vmcnt(3)
	ds_write_b128 v175, v[118:121] offset:9216

; DI unsigned pack2(float a, float b) { f32x2 v = {a, b}; bf16v2 r = __builtin_convertvector(v, bf16v2); return __builtin_bit_cast(unsigned, r); }
; DI f32x16 mfma(bf16x8 a, bf16x8 b, f32x16 c) { return __builtin_amdgcn_mfma_f32_32x32x16_bf16(a, b, c, 0, 0, 0); }
; DI float fexp2(float x) { return __builtin_amdgcn_exp2f(x); }
; template <int MODE>
; DI void attn_tile(const Params& p, int layer, int tile, char* smem) {
;     ...
;       const u16* Kb = Ks + buf * 64 * KROW + r * KROW + 8 * h;
;       const u16* Vb = Vs + buf * 64 * VROW;
;       bf16x8 vf[8];
; #pragma unroll
;       for (int cs2 = 0; cs2 < 4; ++cs2) {
;         const u16* vp = Vb + (16 * cs2 + 4 * h + qq) * VROW + 16 * g16 + 4 * pp4;
;         { s16x4 lo = tr_read(vp), hi = tr_read(vp + 8 * VROW); vf[2 * cs2] = __builtin_shufflevector(lo, hi, 0, 1, 2, 3, 4, 5, 6, 7); }
;         { s16x4 lo = tr_read(vp + 32), hi = tr_read(vp + 8 * VROW + 32); vf[2 * cs2 + 1] = __builtin_shufflevector(lo, hi, 0, 1, 2, 3, 4, 5, 6, 7); }
;       }
;       f32x16 s0 = negm, s1 = negm;
; #pragma unroll
;       for (int d0 = 0; d0 < NKQ; ++d0) {
;         bf16x8 k0 = *(const bf16x8*)(Kb + d0 * 16);
;         bf16x8 k1 = *(const bf16x8*)(Kb + 32 * KROW + d0 * 16);
;         s0 = mfma(k0, qf[d0], s0);
;         s1 = mfma(k1, qf[d0], s1);
;       }
;     ...
;       float ps = 0.f;
; #pragma unroll
;       for (int i = 0; i < 16; ++i) { s0[i] = fexp2(s0[i]); s1[i] = fexp2(s1[i]); ps += s0[i] + s1[i]; }
;       lsum += ps;
; #pragma unroll
;       for (int c = 0; c < 2; ++c) {
; #pragma unroll
;         for (int s = 0; s < 2; ++s) {
;           u32x4 pw;
;           if (c == 0) pw = (u32x4){pack2(s0[8 * s], s0[8 * s + 1]), pack2(s0[8 * s + 2], s0[8 * s + 3]), pack2(s0[8 * s + 4], s0[8 * s + 5]), pack2(s0[8 * s + 6], s0[8 * s + 7])};
;           else pw = (u32x4){pack2(s1[8 * s], s1[8 * s + 1]), pack2(s1[8 * s + 2], s1[8 * s + 3]), pack2(s1[8 * s + 4], s1[8 * s + 5]), pack2(s1[8 * s + 6], s1[8 * s + 7])};
;           const bf16x8 pf = __builtin_bit_cast(bf16x8, pw);
;           o0 = mfma(vf[2 * (2 * c + s)], pf, o0);
;           o1 = mfma(vf[2 * (2 * c + s) + 1], pf, o1);
;         }
;       }
.Lstf_b_r1:
	v_mfma_f32_32x32x16_bf16 v[82:97], v[228:231], v[102:105], v[82:97]
	v_exp_f32_e32 v66, v66
	v_exp_f32_e32 v67, v67
	v_exp_f32_e32 v179, v68
	v_exp_f32_e32 v180, v69
	v_mfma_f32_32x32x16_bf16 v[82:97], v[236:239], v[106:109], v[82:97]
	v_exp_f32_e32 v182, v70
	v_exp_f32_e32 v183, v71
	v_exp_f32_e32 v186, v72
	v_exp_f32_e32 v210, v73
	v_mfma_f32_32x32x16_bf16 v[82:97], v[240:243], v[110:113], v[82:97]
	v_cvt_pk_bf16_f32 v68, v66, v67
	v_cvt_pk_bf16_f32 v69, v179, v180
	v_cvt_pk_bf16_f32 v70, v182, v183
	v_cvt_pk_bf16_f32 v71, v186, v210
	v_exp_f32_e32 v188, v74
	v_exp_f32_e32 v189, v75
	v_exp_f32_e32 v190, v76
	v_exp_f32_e32 v212, v77
	v_exp_f32_e32 v213, v78
	v_exp_f32_e32 v214, v79
	v_exp_f32_e32 v215, v80
	v_exp_f32_e32 v216, v81
	v_exp_f32_e32 v181, v85
	v_exp_f32_e32 v184, v86
	s_waitcnt lgkmcnt(14)
	v_mfma_f32_32x32x16_bf16 v[18:33], v[158:161], v[68:71], v[18:33]
	v_exp_f32_e32 v211, v89
	v_exp_f32_e32 v191, v90
	v_exp_f32_e32 v192, v91
	v_mfma_f32_32x32x16_bf16 v[2:17], v[154:157], v[68:71], v[2:17]
	v_cvt_pk_bf16_f32 v68, v188, v189
	v_cvt_pk_bf16_f32 v69, v190, v212
	v_cvt_pk_bf16_f32 v70, v213, v214
	v_cvt_pk_bf16_f32 v71, v215, v216
	v_exp_f32_e32 v82, v82
	v_exp_f32_e32 v83, v83
	s_waitcnt lgkmcnt(10)
	v_mfma_f32_32x32x16_bf16 v[18:33], v[150:153], v[68:71], v[18:33]
	v_exp_f32_e32 v84, v84
	v_exp_f32_e32 v185, v87
	v_exp_f32_e32 v187, v88
	v_exp_f32_e32 v193, v92
	v_exp_f32_e32 v92, v93
	v_exp_f32_e32 v93, v94
	v_exp_f32_e32 v94, v95
	s_waitcnt lgkmcnt(8)
	v_mfma_f32_32x32x16_bf16 v[2:17], v[146:149], v[68:71], v[2:17]
	v_cvt_pk_bf16_f32 v68, v82, v83
	v_cvt_pk_bf16_f32 v69, v84, v181
	v_cvt_pk_bf16_f32 v70, v184, v185
	v_cvt_pk_bf16_f32 v71, v187, v211
	v_exp_f32_e32 v87, v96
	v_exp_f32_e32 v88, v97
	s_waitcnt lgkmcnt(6)
	v_mfma_f32_32x32x16_bf16 v[18:33], v[142:145], v[68:71], v[18:33]
	s_waitcnt lgkmcnt(4)
	v_mfma_f32_32x32x16_bf16 v[2:17], v[138:141], v[68:71], v[2:17]
	v_cvt_pk_bf16_f32 v68, v191, v192
	v_cvt_pk_bf16_f32 v69, v193, v92
	v_cvt_pk_bf16_f32 v70, v93, v94
	v_cvt_pk_bf16_f32 v71, v87, v88
	s_waitcnt lgkmcnt(2)
	s_nop 0
	v_mfma_f32_32x32x16_bf16 v[18:33], v[130:133], v[68:71], v[18:33]
	s_waitcnt lgkmcnt(0)
	v_mfma_f32_32x32x16_bf16 v[2:17], v[134:137], v[68:71], v[2:17]
	s_cmp_lg_u32 s32, 0
	s_cbranch_scc1 .Lstf_b_n1
	s_barrier
.Lstf_b_n1:
	ds_read_b128 v[130:133], v174 offset:9216
	ds_read_b128 v[134:137], v174 offset:13824
	ds_read_b128 v[138:141], v174 offset:9248
	v_add_f32_e32 v0, v82, v66
	v_add_f32_e32 v82, v83, v67
	s_waitcnt lgkmcnt(2)
	v_mfma_f32_32x32x16_bf16 v[66:81], v[130:133], v[98:101], v[34:49]
	ds_read_b128 v[130:133], v174 offset:13856
	v_add_f32_e32 v0, 0, v0
	v_add_f32_e32 v0, v82, v0
	v_add_f32_e32 v82, v84, v179
	v_add_f32_e32 v0, v82, v0
	v_add_f32_e32 v82, v181, v180
	v_add_f32_e32 v0, v82, v0
	s_waitcnt lgkmcnt(2)
	v_mfma_f32_32x32x16_bf16 v[50:65], v[134:137], v[98:101], v[34:49]
	v_add_f32_e32 v82, v184, v182
	v_add_f32_e32 v0, v82, v0
	v_add_f32_e32 v82, v185, v183
	v_add_f32_e32 v0, v82, v0
	v_add_f32_e32 v82, v187, v186
	ds_read_b128 v[134:137], v174 offset:9280
	v_add_f32_e32 v0, v82, v0
	v_add_f32_e32 v82, v211, v210
	s_waitcnt lgkmcnt(2)
	v_mfma_f32_32x32x16_bf16 v[66:81], v[138:141], v[102:105], v[66:81]
	v_add_f32_e32 v0, v82, v0
	v_add_f32_e32 v82, v191, v188
	v_add_f32_e32 v0, v82, v0
	v_add_f32_e32 v82, v192, v189
	v_add_f32_e32 v0, v82, v0
	v_add_f32_e32 v82, v193, v190
	v_add_f32_e32 v0, v82, v0
	s_waitcnt lgkmcnt(1)
	v_mfma_f32_32x32x16_bf16 v[50:65], v[130:133], v[102:105], v[50:65]
	v_add_f32_e32 v82, v92, v212
	v_add_f32_e32 v0, v82, v0
	v_add_f32_e32 v82, v93, v213
	v_add_f32_e32 v0, v82, v0
	v_add_f32_e32 v82, v94, v214
	ds_read_b128 v[90:93], v174 offset:13888
	ds_read_b128 v[94:97], v174 offset:9312
	ds_read_b128 v[146:149], v174 offset:13920
	s_waitcnt lgkmcnt(3)
	v_mfma_f32_32x32x16_bf16 v[66:81], v[134:137], v[106:109], v[66:81]
	v_add_f32_e32 v0, v82, v0
	v_add_f32_e32 v82, v87, v215
	v_add_f32_e32 v0, v82, v0
	v_add_f32_e32 v82, v88, v216
	v_add_f32_e32 v0, v82, v0
	ds_read_b64_tr_b16 v[142:143], v173 offset:35840
	ds_read_b64_tr_b16 v[144:145], v173 offset:36992
	ds_read_b64_tr_b16 v[140:141], v173 offset:37056
	ds_read_b64_tr_b16 v[138:139], v173 offset:35904
	ds_read_b64_tr_b16 v[134:135], v173 offset:38144
	ds_read_b64_tr_b16 v[136:137], v173 offset:39296
	ds_read_b64_tr_b16 v[132:133], v173 offset:39360
	ds_read_b64_tr_b16 v[130:131], v173 offset:38208
	v_add_f32_e32 v0, v178, v0
	s_waitcnt lgkmcnt(10)
	v_mfma_f32_32x32x16_bf16 v[50:65], v[90:93], v[106:109], v[50:65]
	s_waitcnt lgkmcnt(9)
	v_mfma_f32_32x32x16_bf16 v[66:81], v[94:97], v[110:113], v[66:81]
	ds_read_b64_tr_b16 v[94:95], v173 offset:40448
	ds_read_b64_tr_b16 v[96:97], v173 offset:41600
	ds_read_b64_tr_b16 v[92:93], v173 offset:41664
	ds_read_b64_tr_b16 v[90:91], v173 offset:40512
	ds_read_b64_tr_b16 v[82:83], v173 offset:42752
	ds_read_b64_tr_b16 v[84:85], v173 offset:43904
	ds_read_b64_tr_b16 v[88:89], v173 offset:43968
	ds_read_b64_tr_b16 v[86:87], v173 offset:42816
	s_waitcnt lgkmcnt(14)
	v_mfma_f32_32x32x16_bf16 v[50:65], v[146:149], v[110:113], v[50:65]
	s_and_saveexec_b64 s[0:1], s[6:7]
	s_cbranch_execz .Lstf_b_s0skip
	s_waitcnt vmcnt(3)
	ds_write_b128 v175, v[126:129]
